# attention step second trim: v_bfe for the block-selected bit, SGPR ballot test, four scalar add pairs merged into v_pk_add_f32 (8 fewer VALU per step)
# baseline (speedup 1.0000x reference)
; __device__ void attn_item(const Params& p, char* lds, int bh, int qi) {
;     ...
;   for (int s = 0; s < nsteps; ++s) {
;     if (s + 1 < nsteps) gload(s + 1);
;     const int jb = qi - (s >> 2), sub = s & 3;
;     const bool own = (s < 4);
;     const bool sel = own ? true : ((selmask >> jb) & 1u);
;     bool active;
;     if (own) active = (sub * 64 <= wave * 32 + 31);
;     else active = (__ballot(sel) != 0ull);
.LBB0_417:
	s_lshr_b32 s4, s26, 2
	s_sub_i32 s4, s37, s4
	v_bfe_u32 v34, v105, s4, 1
	s_cmp_lt_u32 s26, 4
	s_cselect_b64 s[22:23], -1, 0
	s_cmp_gt_u32 s26, 3
	v_cmp_eq_u32_e64 s[4:5], 1, v34
	s_mov_b64 s[20:21], -1
	s_cbranch_scc0 .LBB0_419
	s_cmp_lg_u64 s[4:5], 0
	s_mov_b64 s[20:21], 0
	s_cselect_b64 s[28:29], -1, 0

; __device__ void attn_item(const Params& p, char* lds, int bh, int qi) {
;     ...
;   auto fast_step = [&](auto diag_, int s, int sub, bool sel) {
;     constexpr bool DIAG = decltype(diag_)::value;
;     const u16* ks_ = Ks + (s & 1) * 64 * LD + l31 * LD + 8 * h;
;     const u16* vs_ = Vs + (s & 1) * 64 * LD + l31 * LD + 8 * h;
;     f32x16 cb, S0, S1;
;     {
;       const float cinit = sel ? -mref : -INFINITY;
; #pragma unroll
;       for (int r = 0; r < 16; ++r) cb[r] = cinit;
;     }
;     S0 = __builtin_amdgcn_mfma_f32_32x32x16_bf16(*(const bf16x8*)(ks_), qf[0], cb, 0, 0, 0);
; #pragma unroll
;     for (int ks = 1; ks < 4; ++ks) S0 = __builtin_amdgcn_mfma_f32_32x32x16_bf16(*(const bf16x8*)(ks_ + ks * 16), qf[ks], S0, 0, 0, 0);
;     S1 = __builtin_amdgcn_mfma_f32_32x32x16_bf16(*(const bf16x8*)(ks_ + 32 * LD), qf[0], cb, 0, 0, 0);
; #pragma unroll
;     for (int ks = 1; ks < 4; ++ks) S1 = __builtin_amdgcn_mfma_f32_32x32x16_bf16(*(const bf16x8*)(ks_ + 32 * LD + ks * 16), qf[ks], S1, 0, 0, 0);
;     if constexpr (DIAG) {
;       const int qrel = wave * 32 + l31;
; #pragma unroll
;       for (int r = 0; r < 16; ++r) {
;         const int krel = sub * 64 + rm32(r, h);
;         S0[r] = (krel <= qrel) ? S0[r] : -INFINITY;
;         S1[r] = (krel + 32 <= qrel) ? S1[r] : -INFINITY;
;       }
;     }
;     float mx0 = -INFINITY, mx1 = -INFINITY, ps0 = 0.f, ps1 = 0.f;
; #pragma unroll
;     for (int r = 0; r < 16; r += 2) mx0 = fmaxf(fmaxf(mx0, S0[r]), S0[r + 1]);
; #pragma unroll
;     for (int r = 0; r < 16; ++r) { S0[r] = __builtin_amdgcn_exp2f(S0[r]); ps0 += S0[r]; }
; #pragma unroll
;     for (int sp = 0; sp < 2; ++sp) {
;       u32x4 pw;
;       pw.x = pk2(S0[8 * sp + 0], S0[8 * sp + 1]); pw.y = pk2(S0[8 * sp + 2], S0[8 * sp + 3]);
;       pw.z = pk2(S0[8 * sp + 4], S0[8 * sp + 5]); pw.w = pk2(S0[8 * sp + 6], S0[8 * sp + 7]);
;       const bf16x8 pb = __builtin_bit_cast(bf16x8, pw);
; #pragma unroll
;       for (int d = 0; d < 2; ++d) O[d] = __builtin_amdgcn_mfma_f32_32x32x16_bf16(*(const bf16x8*)(vs_ + d * 32 * LD + sp * 16), pb, O[d], 0, 0, 0);
;     }
; #pragma unroll
;     for (int r = 0; r < 16; r += 2) mx1 = fmaxf(fmaxf(mx1, S1[r]), S1[r + 1]);
; #pragma unroll
;     for (int r = 0; r < 16; ++r) { S1[r] = __builtin_amdgcn_exp2f(S1[r]); ps1 += S1[r]; }
; #pragma unroll
;     for (int sp = 0; sp < 2; ++sp) {
;       u32x4 pw;
.Lattn_bias_ok:
	s_waitcnt lgkmcnt(1)
	v_mfma_f32_32x32x16_bf16 v[34:49], v[128:131], v[66:69], v[176:191]
	ds_read_b128 v[128:131], v127 offset:4608
	ds_read_b128 v[136:139], v127 offset:4640
	s_waitcnt lgkmcnt(2)
	v_mfma_f32_32x32x16_bf16 v[34:49], v[132:135], v[70:73], v[34:49]
	s_waitcnt lgkmcnt(1)
	v_mfma_f32_32x32x16_bf16 v[50:65], v[128:131], v[66:69], v[176:191]
	ds_read_b128 v[128:131], v127 offset:64
	ds_read_b128 v[132:135], v127 offset:96
	s_waitcnt lgkmcnt(1)
	v_mfma_f32_32x32x16_bf16 v[34:49], v[128:131], v[74:77], v[34:49]
	ds_read_b128 v[128:131], v127 offset:4704
	v_mfma_f32_32x32x16_bf16 v[50:65], v[136:139], v[70:73], v[50:65]
	s_waitcnt lgkmcnt(1)
	v_mfma_f32_32x32x16_bf16 v[34:49], v[132:135], v[78:81], v[34:49]
	v_mfma_f32_32x32x16_bf16 v[50:65], v[90:93], v[74:77], v[50:65]
	s_nop 10
	v_exp_f32_e32 v140, v34
	v_max3_f32 v34, v34, v35, v36
	v_max3_f32 v34, v34, v37, v38
	v_max3_f32 v34, v34, v39, v40
	v_max3_f32 v34, v34, v41, v42
	s_waitcnt lgkmcnt(0)
	v_mfma_f32_32x32x16_bf16 v[50:65], v[128:131], v[78:81], v[50:65]
	v_exp_f32_e32 v142, v35
	v_exp_f32_e32 v144, v36
	v_exp_f32_e32 v146, v37
	v_exp_f32_e32 v148, v38
	v_exp_f32_e32 v150, v39
	v_exp_f32_e32 v152, v40
	v_exp_f32_e32 v154, v41
	v_max3_f32 v34, v34, v43, v44
	v_exp_f32_e32 v158, v42
	v_exp_f32_e32 v160, v43
	v_exp_f32_e32 v162, v44
	v_exp_f32_e32 v164, v45
	v_max3_f32 v34, v34, v45, v46
	ds_read_b128 v[38:41], v127 offset:18432
	ds_read_b128 v[42:45], v127 offset:23040
	v_exp_f32_e32 v170, v48
	v_max3_f32 v48, v34, v47, v48
	v_cvt_pk_bf16_f32 v34, v140, v142
	v_cvt_pk_bf16_f32 v35, v144, v146
	v_cvt_pk_bf16_f32 v36, v148, v150
	v_cvt_pk_bf16_f32 v37, v152, v154
	v_exp_f32_e32 v166, v46
	v_max3_f32 v46, v50, s34, v51
	s_waitcnt lgkmcnt(1)
	v_mfma_f32_32x32x16_bf16 v[18:33], v[38:41], v[34:37], v[18:33]
	v_max3_f32 v46, v46, v52, v53
	v_exp_f32_e32 v141, v50
	v_max3_f32 v38, v46, v54, v55
	v_exp_f32_e32 v143, v51
	v_exp_f32_e32 v168, v47
	v_exp_f32_e32 v172, v49
	v_max3_f32 v38, v38, v56, v57
	s_waitcnt lgkmcnt(0)
	v_mfma_f32_32x32x16_bf16 v[2:17], v[42:45], v[34:37], v[2:17]
	v_exp_f32_e32 v145, v52
	ds_read_b128 v[128:131], v127 offset:18464
	ds_read_b128 v[132:135], v127 offset:23072
	v_max3_f32 v38, v38, v58, v59
	v_exp_f32_e32 v147, v53
	v_max3_f32 v38, v38, v60, v61
	v_max3_f32 v38, v38, v62, v63
	v_pk_add_f32 v[42:43], v[142:143], v[140:141]
	v_cvt_pk_bf16_f32 v90, v158, v160
	v_cvt_pk_bf16_f32 v91, v162, v164
	v_cvt_pk_bf16_f32 v92, v166, v168
	v_cvt_pk_bf16_f32 v93, v170, v172
	v_max3_f32 v136, v38, v64, v65
	ds_read_b128 v[38:41], v127 offset:18528
	ds_read_b128 v[34:37], v127 offset:18496
	v_pk_add_f32 v[42:43], v[144:145], v[42:43]
	s_waitcnt lgkmcnt(3)
	v_mfma_f32_32x32x16_bf16 v[18:33], v[128:131], v[90:93], v[18:33]
	v_pk_add_f32 v[46:47], v[146:147], v[42:43]
	ds_read_b128 v[42:45], v127 offset:23104
	v_exp_f32_e32 v149, v54
	v_exp_f32_e32 v151, v55
	v_exp_f32_e32 v153, v56
	v_exp_f32_e32 v155, v57
	v_cvt_pk_bf16_f32 v50, v141, v143
	s_waitcnt lgkmcnt(3)
	v_mfma_f32_32x32x16_bf16 v[2:17], v[132:135], v[90:93], v[2:17]
	v_cvt_pk_bf16_f32 v51, v145, v147
	v_cvt_pk_bf16_f32 v52, v149, v151
	v_cvt_pk_bf16_f32 v53, v153, v155
	v_exp_f32_e32 v159, v58
	v_exp_f32_e32 v161, v59
	v_exp_f32_e32 v163, v60
	v_exp_f32_e32 v165, v61
	s_waitcnt lgkmcnt(1)
	v_mfma_f32_32x32x16_bf16 v[18:33], v[34:37], v[50:53], v[18:33]
	v_exp_f32_e32 v167, v62
	v_exp_f32_e32 v169, v63
	v_exp_f32_e32 v171, v64
	v_exp_f32_e32 v173, v65
	v_pk_add_f32 v[46:47], v[148:149], v[46:47]
	v_cvt_pk_bf16_f32 v34, v159, v161
	v_pk_add_f32 v[46:47], v[150:151], v[46:47]
	s_waitcnt lgkmcnt(0)
	v_mfma_f32_32x32x16_bf16 v[2:17], v[42:45], v[50:53], v[2:17]
	ds_read_b128 v[42:45], v127 offset:23136
	v_pk_add_f32 v[46:47], v[152:153], v[46:47]
	v_cvt_pk_bf16_f32 v35, v163, v165
	v_cvt_pk_bf16_f32 v36, v167, v169
	v_cvt_pk_bf16_f32 v37, v171, v173
	v_pk_add_f32 v[46:47], v[154:155], v[46:47]
	s_nop 0
	v_mfma_f32_32x32x16_bf16 v[18:33], v[38:41], v[34:37], v[18:33]
	v_pk_add_f32 v[38:39], v[158:159], v[46:47]
	v_max3_f32 v40, v48, v49, v136
	v_add_f32_e64 v38, v160, v38
	v_add_f32_e64 v39, v161, v39
	v_pk_add_f32 v[38:39], v[162:163], v[38:39]
	s_nop 0
	v_pk_add_f32 v[38:39], v[164:165], v[38:39]
	s_waitcnt lgkmcnt(0)
	v_mfma_f32_32x32x16_bf16 v[2:17], v[42:45], v[34:37], v[2:17]
	v_pk_add_f32 v[38:39], v[166:167], v[38:39]
	ds_bpermute_b32 v36, v192, v40
	v_pk_add_f32 v[38:39], v[168:169], v[38:39]
	s_nop 0
	v_pk_add_f32 v[34:35], v[170:171], v[38:39]
	s_nop 0
	v_pk_add_f32 v[34:35], v[172:173], v[34:35]
	s_nop 0
	v_add_f32_e32 v34, v34, v35
	v_add_f32_e32 v126, v126, v34
	s_waitcnt lgkmcnt(0)
	v_max_f32_e32 v34, v36, v36
	v_max_f32_e32 v34, v40, v34
	v_cmp_lt_f32_e32 vcc, s35, v34
	s_cbranch_vccz .LBB0_439
	s_nop 0
	s_mov_b32 s94, 1
	v_cndmask_b32_e32 v35, 0, v34, vcc
	v_exp_f32_e64 v34, -v35
	v_add_f32_e32 v107, v107, v35
	v_mul_f32_e32 v126, v126, v34
	v_pk_mul_f32 v[32:33], v[32:33], v[34:35] op_sel_hi:[1,0]
	v_pk_mul_f32 v[30:31], v[30:31], v[34:35] op_sel_hi:[1,0]
	v_pk_mul_f32 v[28:29], v[28:29], v[34:35] op_sel_hi:[1,0]
	v_pk_mul_f32 v[26:27], v[26:27], v[34:35] op_sel_hi:[1,0]
	v_pk_mul_f32 v[24:25], v[24:25], v[34:35] op_sel_hi:[1,0]
	v_pk_mul_f32 v[22:23], v[22:23], v[34:35] op_sel_hi:[1,0]
	v_pk_mul_f32 v[20:21], v[20:21], v[34:35] op_sel_hi:[1,0]
	v_pk_mul_f32 v[18:19], v[18:19], v[34:35] op_sel_hi:[1,0]
	v_pk_mul_f32 v[16:17], v[16:17], v[34:35] op_sel_hi:[1,0]
	v_pk_mul_f32 v[14:15], v[14:15], v[34:35] op_sel_hi:[1,0]
	v_pk_mul_f32 v[12:13], v[12:13], v[34:35] op_sel_hi:[1,0]
	v_pk_mul_f32 v[10:11], v[10:11], v[34:35] op_sel_hi:[1,0]
	v_pk_mul_f32 v[8:9], v[8:9], v[34:35] op_sel_hi:[1,0]
	v_pk_mul_f32 v[6:7], v[6:7], v[34:35] op_sel_hi:[1,0]
	v_pk_mul_f32 v[4:5], v[4:5], v[34:35] op_sel_hi:[1,0]
	v_pk_mul_f32 v[2:3], v[2:3], v[34:35] op_sel_hi:[1,0]
